# speedup vs baseline: 1.0009x; 1.0009x over previous
.LBB0_479:
	v_ashrrev_i32_e32 v151, 31, v150
	v_mov_b32_e32 v31, 0
	s_andn2_b64 vcc, exec, s[0:1]
	v_mov_b32_e32 v30, 0
	v_mov_b32_e32 v29, 0
	v_mov_b32_e32 v28, 0
	v_mov_b32_e32 v27, 0
	v_mov_b32_e32 v26, 0
	v_mov_b32_e32 v25, 0
	v_mov_b32_e32 v24, 0
	v_mov_b32_e32 v23, 0
	v_mov_b32_e32 v22, 0
	v_mov_b32_e32 v21, 0
	v_mov_b32_e32 v20, 0
	v_mov_b32_e32 v19, 0
	v_mov_b32_e32 v18, 0
	v_mov_b32_e32 v17, 0
	v_mov_b32_e32 v16, 0
	v_mov_b32_e32 v47, 0
	v_mov_b32_e32 v46, 0
	v_mov_b32_e32 v45, 0
	v_mov_b32_e32 v44, 0
	v_mov_b32_e32 v43, 0
	v_mov_b32_e32 v42, 0
	v_mov_b32_e32 v41, 0
	v_mov_b32_e32 v40, 0
	v_mov_b32_e32 v39, 0
	v_mov_b32_e32 v38, 0
	v_mov_b32_e32 v37, 0
	v_mov_b32_e32 v36, 0
	v_mov_b32_e32 v35, 0
	v_mov_b32_e32 v34, 0
	v_mov_b32_e32 v33, 0
	v_mov_b32_e32 v32, 0
	v_mov_b32_e32 v190, 0
	s_cbranch_vccnz .LBB0_390
	v_lshrrev_b32_e32 v0, 2, v2
	v_lshlrev_b64 v[16:17], 3, v[2:3]
	v_lshlrev_b64 v[18:19], 3, v[4:5]
	v_lshlrev_b32_e32 v2, 1, v2
	v_and_b32_e32 v3, 24, v8
	v_and_or_b32 v0, v0, 3, v189
	v_mov_b32_e32 v14, v1
	v_mov_b32_e32 v15, v1
	v_lshlrev_b64 v[152:153], 3, v[6:7]
	v_and_or_b32 v191, v2, 32, v3
	v_mul_u32_u24_e32 v192, 0xc0, v0
	v_mov_b32_e32 v0, v1
	v_mov_b32_e32 v2, v1
	v_mov_b32_e32 v3, v1
	v_mov_b32_e32 v4, v1
	v_mov_b32_e32 v5, v1
	v_mov_b32_e32 v6, v1
	v_mov_b32_e32 v7, v1
	v_mov_b32_e32 v8, v1
	v_mov_b32_e32 v9, v1
	v_mov_b32_e32 v10, v1
	v_mov_b32_e32 v11, v1
	v_mov_b32_e32 v12, v1
	v_mov_b32_e32 v13, v1
	v_lshlrev_b64 v[154:155], 1, v[16:17]
	v_lshlrev_b64 v[156:157], 1, v[18:19]
	v_mov_b64_e32 v[30:31], v[14:15]
	v_mov_b64_e32 v[46:47], v[14:15]
	v_mov_b64_e32 v[110:111], v[14:15]
	v_mov_b64_e32 v[94:95], v[14:15]
	s_or_b32 s35, s14, 31
	s_mov_b32 s40, 3
	v_mov_b32_e32 v193, 0xff800000
	v_mov_b32_e32 v190, 0
	s_movk_i32 s41, 0x7f
	v_mov_b64_e32 v[28:29], v[12:13]
	v_mov_b64_e32 v[26:27], v[10:11]
	v_mov_b64_e32 v[24:25], v[8:9]
	v_mov_b64_e32 v[22:23], v[6:7]
	v_mov_b64_e32 v[20:21], v[4:5]
	v_mov_b64_e32 v[18:19], v[2:3]
	v_mov_b64_e32 v[16:17], v[0:1]
	v_mov_b64_e32 v[44:45], v[12:13]
	v_mov_b64_e32 v[42:43], v[10:11]
	v_mov_b64_e32 v[40:41], v[8:9]
	v_mov_b64_e32 v[38:39], v[6:7]
	v_mov_b64_e32 v[36:37], v[4:5]
	v_mov_b64_e32 v[34:35], v[2:3]
	v_mov_b64_e32 v[32:33], v[0:1]
	v_mov_b64_e32 v[108:109], v[12:13]
	v_mov_b64_e32 v[106:107], v[10:11]
	v_mov_b64_e32 v[104:105], v[8:9]
	v_mov_b64_e32 v[102:103], v[6:7]
	v_mov_b64_e32 v[100:101], v[4:5]
	v_mov_b64_e32 v[98:99], v[2:3]
	v_mov_b64_e32 v[96:97], v[0:1]
	v_mov_b64_e32 v[92:93], v[12:13]
	v_mov_b64_e32 v[90:91], v[10:11]
	v_mov_b64_e32 v[88:89], v[8:9]
	v_mov_b64_e32 v[86:87], v[6:7]
	v_mov_b64_e32 v[84:85], v[4:5]
	v_mov_b64_e32 v[82:83], v[2:3]
	v_mov_b64_e32 v[80:81], v[0:1]
	s_cmp_gt_i32 s15, 2
	s_cselect_b32 s100, 2, 0
	s_mul_hi_u32 s47, s100, 0x3000
	s_mul_i32 s46, s100, 0x3000
	s_add_u32 s46, s6, s46
	s_addc_u32 s47, s7, s47
	s_add_u32 s48, s8, 0x2000
	s_addc_u32 s49, s9, 0
	v_lshl_add_u64 v[210:211], s[46:47], 0, v[154:155]
	v_lshl_add_u64 v[214:215], s[46:47], 0, v[156:157]
	v_lshl_add_u64 v[218:219], v[152:153], 1, s[46:47]
	v_lshl_add_u64 v[222:223], s[48:49], 0, v[154:155]
	v_lshl_add_u64 v[226:227], s[48:49], 0, v[156:157]
	global_load_dwordx4 v[210:213], v[210:211], off
	s_nop 0
	global_load_dwordx4 v[214:217], v[214:215], off
	s_nop 0
	global_load_dwordx4 v[218:221], v[218:219], off
	s_nop 0
	global_load_dwordx4 v[222:225], v[222:223], off
	s_nop 0
	global_load_dwordx4 v[226:229], v[226:227], off
	s_branch .LBB0_483
	s_nop 0
	s_nop 0
	s_nop 0
	s_nop 0
	s_nop 0
	s_nop 0
	s_nop 0
	s_nop 0

.LBB0_482:
	s_add_i32 s40, s40, 2
	s_addk_i32 s41, 0x80
	s_cmp_lt_i32 s44, s15
	s_waitcnt vmcnt(9)
	ds_write_b128 v186, v[2:5] offset:13312
	s_waitcnt vmcnt(8)
	ds_write_b128 v187, v[6:9] offset:13312
	s_waitcnt vmcnt(7)
	ds_write_b128 v188, v[10:13] offset:13312
	s_waitcnt vmcnt(6)
	ds_write_b128 v158, v[136:139] offset:26624
	s_waitcnt vmcnt(5)
	ds_write_b128 v158, v[140:143] offset:32768
	s_waitcnt lgkmcnt(0)
	s_barrier
	s_cbranch_scc0 .LBB0_389
	s_nop 0
	s_nop 0
	s_nop 0
	s_nop 0
	s_nop 0
	s_nop 0
	s_nop 0
	s_nop 0
	s_nop 0
	s_nop 0
